# bar_nowb + na_waits + P1 rotation 18
# baseline (speedup 1.0000x reference)
.LBB0_103:
	s_cmp_lt_i32 s82, 2
	s_cselect_b64 s[4:5], -1, 0
	s_add_u32 s6, s80, 0x1100000
	v_writelane_b32 v255, s84, 25
	s_addc_u32 s7, s81, 0
	v_writelane_b32 v255, s6, 26
	s_nop 1
	v_writelane_b32 v255, s7, 27
	s_add_u32 s6, s80, 0x1300000
	s_addc_u32 s7, s81, 0
	v_writelane_b32 v255, s6, 28
	s_nop 1
	v_writelane_b32 v255, s7, 29
	s_add_u32 s6, s80, 0x1b00000
	s_addc_u32 s7, s81, 0
	s_add_u32 s69, s80, 0x2600000
	v_writelane_b32 v255, s6, 30
	s_addc_u32 s70, s81, 0
	s_nop 0
	v_writelane_b32 v255, s7, 31
	s_add_u32 s6, s80, 0x2c00000
	s_addc_u32 s7, s81, 0
	s_add_u32 s60, s80, 0x8c00000
	s_addc_u32 s61, s81, 0
	s_add_u32 s96, s80, 0xdc00000
	s_addc_u32 s91, s81, 0
	s_add_u32 s62, s80, 0x7c00000
	v_writelane_b32 v255, s6, 32
	s_addc_u32 s63, s81, 0
	s_and_b64 s[28:29], s[4:5], s[0:1]
	v_writelane_b32 v255, s7, 33
	s_andn2_b64 vcc, exec, s[28:29]
	s_cbranch_vccnz .LBB0_220
	s_cmpk_lt_i32 s2, 0x590
	s_cselect_b64 s[4:5], -1, 0
	s_cmpk_gt_i32 s2, 0x58f
	v_readfirstlane_b32 s6, v216
	s_cbranch_scc1 .LBB0_107
	s_cmpk_gt_i32 s2, 0x57f
	s_cbranch_scc1 .LBB0_108
	s_ashr_i32 s0, s2, 31
	s_lshr_b32 s0, s0, 29
	s_add_i32 s0, s2, s0
	s_ashr_i32 s1, s0, 3
	s_and_b32 s0, s0, -8
	s_sub_i32 s0, s2, s0
	s_cmp_lt_i32 s0, 0
	s_movk_i32 s7, 0xb1
	s_cselect_b32 s7, s7, 0xb0
	s_mul_i32 s0, s0, s7
	s_add_i32 s0, s0, s1
	s_mul_hi_i32 s1, s0, 0x2e8ba2e9
	s_lshr_b32 s7, s1, 31
	s_ashr_i32 s1, s1, 5
	s_add_i32 s1, s1, s7
	s_lshl_b32 s7, s1, 3
	s_mulk_i32 s1, 0xb0
	s_sub_i32 s0, s0, s1
	s_sext_i32_i16 s1, s0
	s_bfe_u32 s1, s1, 0x3001c
	s_add_i32 s1, s0, s1
	s_bfe_u32 s8, s1, 0xd0003
	s_and_b32 s1, s1, 0xfff8
	s_sub_i32 s0, s0, s1
	s_sext_i32_i16 s0, s0
	s_add_i32 s8, s8, 18
	s_add_i32 s38, s7, s0
	s_bfe_i32 s0, s8, 0x80000
	s_mul_i32 s0, s0, 0xffbb
	s_bfe_u32 s0, s0, 0x80008
	s_add_i32 s0, s0, s8
	s_bfe_i32 s1, s0, 0x80000
	s_and_b32 s1, 0xffff, s1
	s_lshr_b32 s1, s1, 4
	s_bfe_u32 s0, s0, 0x10007
	s_add_i32 s0, s1, s0
	s_mul_i32 s0, s0, 22
	s_sub_i32 s0, s8, s0
	s_mov_b32 s59, 0
	s_sext_i32_i8 s90, s0
	s_mov_b64 s[0:1], -1
	s_andn2_b64 vcc, exec, s[4:5]
	v_lshlrev_b32_e32 v16, 2, v216
	s_cbranch_vccz .LBB0_109
	s_branch .LBB0_178

.LBB0_117:
	s_andn2_b64 vcc, exec, s[12:13]
	s_mov_b32 s69, 1
	s_cbranch_vccnz .LBB0_119
	s_ashr_i32 s5, s4, 31
	s_lshr_b32 s5, s5, 29
	s_add_i32 s5, s4, s5
	s_ashr_i32 s12, s5, 3
	s_and_b32 s5, s5, -8
	s_sub_i32 s4, s4, s5
	s_cmp_lt_i32 s4, 0
	s_movk_i32 s5, 0xb1
	s_cselect_b32 s5, s5, 0xb0
	s_mul_i32 s4, s4, s5
	s_add_i32 s4, s4, s12
	s_mul_hi_i32 s5, s4, 0x2e8ba2e9
	s_lshr_b32 s12, s5, 31
	s_ashr_i32 s5, s5, 5
	s_add_i32 s5, s5, s12
	s_lshl_b32 s12, s5, 3
	s_sub_i32 s13, 64, s12
	s_min_i32 s13, s13, 8
	s_abs_i32 s14, s13
	v_cvt_f32_u32_e32 v0, s14
	s_sub_i32 s16, 0, s14
	s_mulk_i32 s5, 0xb0
	s_sub_i32 s4, s4, s5
	v_rcp_iflag_f32_e32 v0, v0
	s_abs_i32 s5, s4
	s_xor_b32 s15, s4, s13
	s_ashr_i32 s15, s15, 31
	v_mul_f32_e32 v0, 0x4f7ffffe, v0
	v_cvt_u32_f32_e32 v0, v0
	s_mov_b32 s69, 0
	v_readfirstlane_b32 s17, v0
	s_mul_i32 s16, s16, s17
	s_mul_hi_u32 s16, s17, s16
	s_add_i32 s17, s17, s16
	s_mul_hi_u32 s16, s5, s17
	s_mul_i32 s17, s16, s14
	s_sub_i32 s5, s5, s17
	s_add_i32 s17, s16, 1
	s_sub_i32 s18, s5, s14
	s_cmp_ge_u32 s5, s14
	s_cselect_b32 s16, s17, s16
	s_cselect_b32 s5, s18, s5
	s_add_i32 s17, s16, 1
	s_cmp_ge_u32 s5, s14
	s_cselect_b32 s5, s17, s16
	s_xor_b32 s5, s5, s15
	s_sub_i32 s5, s5, s15
	s_mul_i32 s13, s5, s13
	s_sub_i32 s4, s4, s13
	s_add_i32 s5, s5, 18
	s_add_i32 s42, s12, s4
	s_sext_i32_i16 s4, s5
	s_mulk_i32 s4, 0xba3
	s_lshr_b32 s12, s4, 31
	s_lshr_b32 s4, s4, 16
	s_add_i32 s4, s4, s12
	s_mul_i32 s4, s4, 22
	s_sub_i32 s4, s5, s4
	s_sext_i32_i16 s44, s4
